# RWKV scan loop: v-address add moved to the back edge (s_nop keeps the DPP spacing) and the last v_mov copy replaced by an op_sel broadcast
# baseline (speedup 1.0000x reference)
; __device__ __forceinline__ void phase_rwkv(KP P, int l_, unsigned char* shm) {
;     ...
;             if (scanw) {
;                 const float* cf = sCoef + (c & 1) * CS; const float* vb = sV + (c % 3) * T * 64; float* ob = sO + (c & 1) * T * 64;
;     ...
;                 RW_LD(A, 0);
; #pragma unroll 2
;                 for (int tl = 0; tl < T; tl += 2) {
;                     RW_LD(B, tl + 1);
.LBB0_2515:
	s_and_b32 s1, s42, 1
	s_waitcnt vmcnt(26)
	v_cndmask_b32_e64 v0, 0, 1, s[78:79]
	s_mov_b32 s0, 0xa000
	s_mul_i32 s1, s1, 0xa000
	s_mul_i32 s43, s42, 0xab
	v_lshl_or_b32 v253, v0, 13, v173
	v_and_b32_e32 v187, 3, v228
	v_lshl_add_u32 v253, v187, 8, v253
	v_add_u32_e32 v253, 0x1e000, v253
	s_mov_b32 s98, 0xaaaaaaaa
	s_mov_b32 s99, 0xaaaaaaaa
	s_mov_b32 s100, 0xcccccccc
	s_mov_b32 s101, 0xcccccccc
	v_mul_lo_u32 v0, v0, s0
	s_bfe_u32 s43, s43, 0x70009
	s_waitcnt vmcnt(17)
	v_add_u32_e32 v14, s1, v156
	v_or_b32_e32 v235, v174, v0
	s_mul_i32 s43, s43, 3
	s_waitcnt vmcnt(12)
	ds_read_b128 v[10:13], v14
	ds_read_b128 v[0:3], v14 offset:16
	s_waitcnt vmcnt(0)
	ds_read_b128 v[38:41], v14 offset:8192
	ds_read_b128 v[34:37], v14 offset:8208
	ds_read_b128 v[26:29], v14 offset:16384
	ds_read_b128 v[6:9], v14 offset:16400
	ds_read_b128 v[30:33], v14 offset:24576
	ds_read_b128 v[22:25], v14 offset:24592
	s_sub_i32 s43, s42, s43
	s_and_b32 s43, s43, 0xff
	s_lshl_b32 s43, s43, 13
	s_add_i32 s43, s43, 0
	v_lshl_add_u32 v4, v123, 2, s43
	v_add_u32_e32 v4, 0x14000, v4
	s_mul_hi_u32 s0, s42, 0xaaaaaaab
	ds_read2_b32 v[106:107], v4 offset1:32
	ds_read_b128 v[18:21], v14 offset:32768
	ds_read_b128 v[14:17], v14 offset:32784
	s_lshr_b32 s0, s0, 1
	s_mulk_i32 s0, 0xa000
	s_add_i32 s43, s0, 0
	s_mov_b32 s52, -2
	v_add_u32_e32 v186, s43, v175
	s_waitcnt lgkmcnt(2)
	s_branch .LBB0_2517
.LBB0_2516:
	s_add_i32 s52, s52, 4
	v_add_u32_e32 v253, 0x400, v253
	v_add_u32_e32 v235, 0x400, v235
	s_cmp_gt_u32 s52, 29
	v_add_u32_e32 v186, 0x400, v186
	s_cbranch_scc1 .LBB0_2489
.LBB0_2517:
	v_pk_mul_f32 v[110:111], v[40:41], v[92:93]
	v_pk_mul_f32 v[40:41], v[40:41], v[100:101]
	v_pk_fma_f32 v[110:111], v[38:39], v[90:91], v[110:111]
	v_pk_fma_f32 v[38:39], v[38:39], v[98:99], v[40:41]
	v_pk_fma_f32 v[40:41], v[36:37], v[96:97], v[110:111]
	v_pk_fma_f32 v[36:37], v[36:37], v[104:105], v[38:39]
	v_pk_fma_f32 v[40:41], v[34:35], v[94:95], v[40:41]
	v_pk_fma_f32 v[34:35], v[34:35], v[102:103], v[36:37]
	v_add_f32_e32 v36, v40, v41
	v_add_f32_e32 v34, v34, v35
	ds_read_b128 v[62:65], v235
	v_add_f32_dpp v35, v36, v36 quad_perm:[1,0,3,2] row_mask:0xf bank_mask:0xf bound_ctrl:1
	v_add_f32_dpp v34, v34, v34 quad_perm:[1,0,3,2] row_mask:0xf bank_mask:0xf bound_ctrl:1
	ds_read_b128 v[50:53], v235 offset:16
	ds_read_b128 v[78:81], v235 offset:8192
	ds_read_b128 v[74:77], v235 offset:8208
	ds_read_b128 v[66:69], v235 offset:16384
	ds_read_b128 v[54:57], v235 offset:16400
	ds_read_b128 v[70:73], v235 offset:24576
	ds_read_b128 v[58:61], v235 offset:24592
	ds_read_b128 v[46:49], v235 offset:32768
	ds_read_b128 v[42:45], v235 offset:32784
	v_add_f32_dpp v35, v35, v35 quad_perm:[2,3,0,1] row_mask:0xf bank_mask:0xf bound_ctrl:1
	v_add_f32_dpp v36, v34, v34 quad_perm:[2,3,0,1] row_mask:0xf bank_mask:0xf bound_ctrl:1
	s_nop 0
	v_add_f32_dpp v34, v35, v35 row_half_mirror row_mask:0xf bank_mask:0xf bound_ctrl:1
	v_add_f32_dpp v36, v36, v36 row_half_mirror row_mask:0xf bank_mask:0xf bound_ctrl:1
	v_pk_mul_f32 v[38:39], v[26:27], v[34:35] op_sel_hi:[1,0] neg_lo:[0,1] neg_hi:[0,1]
	v_pk_mul_f32 v[26:27], v[26:27], v[36:37] op_sel_hi:[1,0] neg_lo:[0,1] neg_hi:[0,1]
	v_pk_fma_f32 v[38:39], v[10:11], v[90:91], v[38:39]
	v_pk_fma_f32 v[10:11], v[10:11], v[98:99], v[26:27]
	s_waitcnt lgkmcnt(13)
	v_pk_fma_f32 v[110:111], v[30:31], v[106:107], v[38:39] op_sel_hi:[1,0,1]
	v_pk_fma_f32 v[98:99], v[30:31], v[106:107], v[10:11] op_sel:[0,1,0]
	v_pk_mul_f32 v[10:11], v[28:29], v[34:35] op_sel_hi:[1,0] neg_lo:[0,1] neg_hi:[0,1]
	v_pk_mul_f32 v[170:171], v[28:29], v[36:37] op_sel_hi:[1,0] neg_lo:[0,1] neg_hi:[0,1]
	ds_read2_b32 v[108:109], v186 offset1:32
	v_pk_fma_f32 v[10:11], v[12:13], v[92:93], v[10:11]
	v_pk_fma_f32 v[170:171], v[12:13], v[100:101], v[170:171]
	v_pk_fma_f32 v[92:93], v[32:33], v[106:107], v[10:11] op_sel_hi:[1,0,1]
	v_pk_fma_f32 v[100:101], v[32:33], v[106:107], v[170:171] op_sel:[0,1,0]
	v_pk_mul_f32 v[10:11], v[6:7], v[34:35] op_sel_hi:[1,0] neg_lo:[0,1] neg_hi:[0,1]
	v_pk_mul_f32 v[6:7], v[6:7], v[36:37] op_sel_hi:[1,0] neg_lo:[0,1] neg_hi:[0,1]
	v_pk_fma_f32 v[10:11], v[0:1], v[94:95], v[10:11]
	v_pk_fma_f32 v[0:1], v[0:1], v[102:103], v[6:7]
	s_waitcnt lgkmcnt(13)
	v_pk_fma_f32 v[94:95], v[22:23], v[106:107], v[10:11] op_sel_hi:[1,0,1]
	v_pk_fma_f32 v[102:103], v[22:23], v[106:107], v[0:1] op_sel:[0,1,0]
	v_pk_mul_f32 v[0:1], v[8:9], v[34:35] op_sel_hi:[1,0] neg_lo:[0,1] neg_hi:[0,1]
	v_pk_mul_f32 v[170:171], v[8:9], v[36:37] op_sel_hi:[1,0] neg_lo:[0,1] neg_hi:[0,1]
	v_pk_fma_f32 v[0:1], v[2:3], v[96:97], v[0:1]
	v_pk_fma_f32 v[170:171], v[2:3], v[104:105], v[170:171]
	v_pk_fma_f32 v[96:97], v[24:25], v[106:107], v[0:1] op_sel_hi:[1,0,1]
	v_pk_fma_f32 v[104:105], v[24:25], v[106:107], v[170:171] op_sel:[0,1,0]
	s_waitcnt lgkmcnt(11)
	v_pk_mul_f32 v[2:3], v[20:21], v[100:101]
	v_pk_mul_f32 v[0:1], v[20:21], v[92:93]
	v_pk_fma_f32 v[2:3], v[18:19], v[98:99], v[2:3]
	v_pk_fma_f32 v[0:1], v[18:19], v[110:111], v[0:1]
	v_pk_fma_f32 v[8:9], v[16:17], v[104:105], v[2:3]
	v_pk_fma_f32 v[6:7], v[16:17], v[96:97], v[0:1]
	v_pk_fma_f32 v[8:9], v[14:15], v[102:103], v[8:9]
	v_pk_fma_f32 v[6:7], v[14:15], v[94:95], v[6:7]
	v_add_f32_e32 v158, v8, v9
	v_add_f32_e32 v157, v6, v7
	s_waitcnt lgkmcnt(6)
	v_pk_mul_f32 v[106:107], v[80:81], v[92:93]
	v_pk_mul_f32 v[80:81], v[80:81], v[100:101]
	v_pk_fma_f32 v[106:107], v[78:79], v[110:111], v[106:107]
	v_pk_fma_f32 v[78:79], v[78:79], v[98:99], v[80:81]
	s_waitcnt lgkmcnt(5)
	v_pk_fma_f32 v[80:81], v[76:77], v[96:97], v[106:107]
	v_pk_fma_f32 v[76:77], v[76:77], v[104:105], v[78:79]
	v_pk_fma_f32 v[80:81], v[74:75], v[94:95], v[80:81]
	v_pk_fma_f32 v[74:75], v[74:75], v[102:103], v[76:77]
	v_add_f32_e32 v4, v80, v81
	v_add_f32_e32 v74, v74, v75
	s_waitcnt lgkmcnt(0)
	v_add_f32_dpp v4, v4, v4 quad_perm:[1,0,3,2] row_mask:0xf bank_mask:0xf bound_ctrl:1
	v_add_f32_dpp v74, v74, v74 quad_perm:[1,0,3,2] row_mask:0xf bank_mask:0xf bound_ctrl:1
	ds_read_b128 v[22:25], v235 offset:256
	ds_read_b128 v[10:13], v235 offset:272
	ds_read_b128 v[38:41], v235 offset:8448
	ds_read_b128 v[34:37], v235 offset:8464
	ds_read_b128 v[26:29], v235 offset:16640
	ds_read_b128 v[14:17], v235 offset:16656
	ds_read_b128 v[30:33], v235 offset:24832
	ds_read_b128 v[18:21], v235 offset:24848
	ds_read_b128 v[6:9], v235 offset:33024
	ds_read_b128 v[0:3], v235 offset:33040
	ds_read2_b32 v[90:91], v186 offset0:64 offset1:96
	v_add_f32_dpp v4, v4, v4 quad_perm:[2,3,0,1] row_mask:0xf bank_mask:0xf bound_ctrl:1
	v_add_f32_dpp v74, v74, v74 quad_perm:[2,3,0,1] row_mask:0xf bank_mask:0xf bound_ctrl:1
	s_nop 0
	v_add_f32_dpp v4, v4, v4 row_half_mirror row_mask:0xf bank_mask:0xf bound_ctrl:1
	v_add_f32_dpp v74, v74, v74 row_half_mirror row_mask:0xf bank_mask:0xf bound_ctrl:1
	v_pk_mul_f32 v[78:79], v[66:67], v[4:5] op_sel_hi:[1,0] neg_lo:[0,1] neg_hi:[0,1]
	v_pk_mul_f32 v[66:67], v[66:67], v[74:75] op_sel_hi:[1,0] neg_lo:[0,1] neg_hi:[0,1]
	v_pk_fma_f32 v[78:79], v[62:63], v[110:111], v[78:79]
	v_pk_fma_f32 v[62:63], v[62:63], v[98:99], v[66:67]
	v_pk_fma_f32 v[106:107], v[70:71], v[108:109], v[78:79] op_sel_hi:[1,0,1]
	v_pk_fma_f32 v[98:99], v[70:71], v[108:109], v[62:63] op_sel:[0,1,0]
	v_pk_mul_f32 v[62:63], v[68:69], v[4:5] op_sel_hi:[1,0] neg_lo:[0,1] neg_hi:[0,1]
	v_pk_mul_f32 v[170:171], v[68:69], v[74:75] op_sel_hi:[1,0] neg_lo:[0,1] neg_hi:[0,1]
	v_pk_fma_f32 v[62:63], v[64:65], v[92:93], v[62:63]
	v_pk_fma_f32 v[170:171], v[64:65], v[100:101], v[170:171]
	v_pk_fma_f32 v[110:111], v[72:73], v[108:109], v[62:63] op_sel_hi:[1,0,1]
	v_pk_fma_f32 v[112:113], v[72:73], v[108:109], v[170:171] op_sel:[0,1,0]
	v_pk_mul_f32 v[62:63], v[54:55], v[4:5] op_sel_hi:[1,0] neg_lo:[0,1] neg_hi:[0,1]
	v_pk_mul_f32 v[54:55], v[54:55], v[74:75] op_sel_hi:[1,0] neg_lo:[0,1] neg_hi:[0,1]
	v_pk_fma_f32 v[62:63], v[50:51], v[94:95], v[62:63]
	v_pk_fma_f32 v[50:51], v[50:51], v[102:103], v[54:55]
	v_pk_fma_f32 v[114:115], v[58:59], v[108:109], v[62:63] op_sel_hi:[1,0,1]
	v_pk_fma_f32 v[116:117], v[58:59], v[108:109], v[50:51] op_sel:[0,1,0]
	v_pk_mul_f32 v[50:51], v[56:57], v[4:5] op_sel_hi:[1,0] neg_lo:[0,1] neg_hi:[0,1]
	v_pk_mul_f32 v[170:171], v[56:57], v[74:75] op_sel_hi:[1,0] neg_lo:[0,1] neg_hi:[0,1]
	v_pk_fma_f32 v[50:51], v[52:53], v[96:97], v[50:51]
	v_pk_fma_f32 v[170:171], v[52:53], v[104:105], v[170:171]
	v_pk_fma_f32 v[118:119], v[60:61], v[108:109], v[50:51] op_sel_hi:[1,0,1]
	v_pk_fma_f32 v[120:121], v[60:61], v[108:109], v[170:171] op_sel:[0,1,0]
	v_pk_mul_f32 v[50:51], v[48:49], v[110:111]
	v_pk_mul_f32 v[48:49], v[48:49], v[112:113]
	v_pk_fma_f32 v[50:51], v[46:47], v[106:107], v[50:51]
	v_pk_fma_f32 v[46:47], v[46:47], v[98:99], v[48:49]
	v_pk_fma_f32 v[48:49], v[44:45], v[118:119], v[50:51]
	v_pk_fma_f32 v[44:45], v[44:45], v[120:121], v[46:47]
	v_pk_fma_f32 v[48:49], v[42:43], v[114:115], v[48:49]
	v_pk_fma_f32 v[42:43], v[42:43], v[116:117], v[44:45]
	v_add_f32_e32 v159, v48, v49
	v_add_f32_e32 v160, v42, v43
	s_waitcnt lgkmcnt(6)
	v_pk_mul_f32 v[92:93], v[40:41], v[110:111]
	v_pk_mul_f32 v[40:41], v[40:41], v[112:113]
	v_pk_fma_f32 v[92:93], v[38:39], v[106:107], v[92:93]
	v_pk_fma_f32 v[38:39], v[38:39], v[98:99], v[40:41]
	s_waitcnt lgkmcnt(5)
	v_pk_fma_f32 v[40:41], v[36:37], v[118:119], v[92:93]
	v_pk_fma_f32 v[36:37], v[36:37], v[120:121], v[38:39]
	v_pk_fma_f32 v[40:41], v[34:35], v[114:115], v[40:41]
	v_pk_fma_f32 v[34:35], v[34:35], v[116:117], v[36:37]
	v_add_f32_e32 v4, v40, v41
	v_add_f32_e32 v34, v34, v35
	s_waitcnt lgkmcnt(0)
	v_add_f32_dpp v4, v4, v4 quad_perm:[1,0,3,2] row_mask:0xf bank_mask:0xf bound_ctrl:1
	v_add_f32_dpp v34, v34, v34 quad_perm:[1,0,3,2] row_mask:0xf bank_mask:0xf bound_ctrl:1
	ds_read_b128 v[62:65], v235 offset:512
	ds_read_b128 v[50:53], v235 offset:528
	ds_read_b128 v[78:81], v235 offset:8704
	ds_read_b128 v[74:77], v235 offset:8720
	ds_read_b128 v[66:69], v235 offset:16896
	ds_read_b128 v[54:57], v235 offset:16912
	ds_read_b128 v[70:73], v235 offset:25088
	ds_read_b128 v[58:61], v235 offset:25104
	ds_read_b128 v[46:49], v235 offset:33280
	ds_read_b128 v[42:45], v235 offset:33296
	ds_read2_b32 v[96:97], v186 offset0:128 offset1:160
	v_add_f32_dpp v4, v4, v4 quad_perm:[2,3,0,1] row_mask:0xf bank_mask:0xf bound_ctrl:1
	v_add_f32_dpp v34, v34, v34 quad_perm:[2,3,0,1] row_mask:0xf bank_mask:0xf bound_ctrl:1
	s_nop 0
	v_add_f32_dpp v4, v4, v4 row_half_mirror row_mask:0xf bank_mask:0xf bound_ctrl:1
	v_add_f32_dpp v34, v34, v34 row_half_mirror row_mask:0xf bank_mask:0xf bound_ctrl:1
	v_pk_mul_f32 v[38:39], v[26:27], v[4:5] op_sel_hi:[1,0] neg_lo:[0,1] neg_hi:[0,1]
	v_pk_mul_f32 v[26:27], v[26:27], v[34:35] op_sel_hi:[1,0] neg_lo:[0,1] neg_hi:[0,1]
	v_pk_fma_f32 v[38:39], v[22:23], v[106:107], v[38:39]
	v_pk_fma_f32 v[22:23], v[22:23], v[98:99], v[26:27]
	v_pk_fma_f32 v[92:93], v[30:31], v[90:91], v[38:39] op_sel_hi:[1,0,1]
	v_pk_fma_f32 v[94:95], v[30:31], v[90:91], v[22:23] op_sel:[0,1,0]
	v_pk_mul_f32 v[22:23], v[28:29], v[4:5] op_sel_hi:[1,0] neg_lo:[0,1] neg_hi:[0,1]
	v_pk_mul_f32 v[170:171], v[28:29], v[34:35] op_sel_hi:[1,0] neg_lo:[0,1] neg_hi:[0,1]
	v_pk_fma_f32 v[22:23], v[24:25], v[110:111], v[22:23]
	v_pk_fma_f32 v[170:171], v[24:25], v[112:113], v[170:171]
	v_pk_fma_f32 v[100:101], v[32:33], v[90:91], v[22:23] op_sel_hi:[1,0,1]
	v_pk_fma_f32 v[102:103], v[32:33], v[90:91], v[170:171] op_sel:[0,1,0]
	v_pk_mul_f32 v[22:23], v[14:15], v[4:5] op_sel_hi:[1,0] neg_lo:[0,1] neg_hi:[0,1]
	v_pk_mul_f32 v[14:15], v[14:15], v[34:35] op_sel_hi:[1,0] neg_lo:[0,1] neg_hi:[0,1]
	v_pk_fma_f32 v[22:23], v[10:11], v[114:115], v[22:23]
	v_pk_fma_f32 v[10:11], v[10:11], v[116:117], v[14:15]
	v_pk_fma_f32 v[104:105], v[18:19], v[90:91], v[22:23] op_sel_hi:[1,0,1]
	v_pk_fma_f32 v[108:109], v[18:19], v[90:91], v[10:11] op_sel:[0,1,0]
	v_pk_mul_f32 v[10:11], v[16:17], v[4:5] op_sel_hi:[1,0] neg_lo:[0,1] neg_hi:[0,1]
	v_pk_mul_f32 v[170:171], v[16:17], v[34:35] op_sel_hi:[1,0] neg_lo:[0,1] neg_hi:[0,1]
	v_pk_fma_f32 v[10:11], v[12:13], v[118:119], v[10:11]
	v_pk_fma_f32 v[170:171], v[12:13], v[120:121], v[170:171]
	v_pk_fma_f32 v[110:111], v[20:21], v[90:91], v[10:11] op_sel_hi:[1,0,1]
	v_pk_fma_f32 v[112:113], v[20:21], v[90:91], v[170:171] op_sel:[0,1,0]
	v_pk_mul_f32 v[10:11], v[8:9], v[100:101]
	v_pk_mul_f32 v[8:9], v[8:9], v[102:103]
	v_pk_fma_f32 v[10:11], v[6:7], v[92:93], v[10:11]
	v_pk_fma_f32 v[6:7], v[6:7], v[94:95], v[8:9]
	v_pk_fma_f32 v[8:9], v[2:3], v[110:111], v[10:11]
	v_pk_fma_f32 v[2:3], v[2:3], v[112:113], v[6:7]
	v_pk_fma_f32 v[8:9], v[0:1], v[104:105], v[8:9]
	v_pk_fma_f32 v[0:1], v[0:1], v[108:109], v[2:3]
	v_add_f32_e32 v161, v8, v9
	v_add_f32_e32 v162, v0, v1
	s_waitcnt lgkmcnt(6)
; __device__ __forceinline__ void phase_rwkv(KP P, int l_, unsigned char* shm) {
;     ...
;                 for (int tl = 0; tl < T; tl += 2) {
;                     RW_LD(B, tl + 1);
;                     RW_STEP(A, tl);
;                     RW_LD(A, tl + 2);
;                     RW_STEP(B, tl + 1);
;                 }
	v_pk_mul_f32 v[90:91], v[80:81], v[100:101]
	v_pk_mul_f32 v[80:81], v[80:81], v[102:103]
	v_pk_fma_f32 v[90:91], v[78:79], v[92:93], v[90:91]
	v_pk_fma_f32 v[78:79], v[78:79], v[94:95], v[80:81]
	s_waitcnt lgkmcnt(5)
	v_pk_fma_f32 v[80:81], v[76:77], v[110:111], v[90:91]
	v_pk_fma_f32 v[76:77], v[76:77], v[112:113], v[78:79]
	v_pk_fma_f32 v[80:81], v[74:75], v[104:105], v[80:81]
	v_pk_fma_f32 v[74:75], v[74:75], v[108:109], v[76:77]
	v_add_f32_e32 v76, v80, v81
	v_add_f32_e32 v74, v74, v75
	s_waitcnt lgkmcnt(0)
	v_add_f32_dpp v75, v76, v76 quad_perm:[1,0,3,2] row_mask:0xf bank_mask:0xf bound_ctrl:1
	v_add_f32_dpp v74, v74, v74 quad_perm:[1,0,3,2] row_mask:0xf bank_mask:0xf bound_ctrl:1
	ds_read_b128 v[10:13], v235 offset:768
	ds_read_b128 v[0:3], v235 offset:784
	ds_read_b128 v[38:41], v235 offset:8960
	ds_read_b128 v[34:37], v235 offset:8976
	ds_read_b128 v[26:29], v235 offset:17152
	ds_read_b128 v[6:9], v235 offset:17168
	ds_read2_b32 v[106:107], v186 offset0:192 offset1:224
	ds_read_b128 v[30:33], v235 offset:25344
	ds_read_b128 v[22:25], v235 offset:25360
	ds_read_b128 v[18:21], v235 offset:33536
	ds_read_b128 v[14:17], v235 offset:33552
	v_add_f32_dpp v75, v75, v75 quad_perm:[2,3,0,1] row_mask:0xf bank_mask:0xf bound_ctrl:1
	v_add_f32_dpp v76, v74, v74 quad_perm:[2,3,0,1] row_mask:0xf bank_mask:0xf bound_ctrl:1
	s_waitcnt lgkmcnt(4)
	v_add_f32_dpp v74, v75, v75 row_half_mirror row_mask:0xf bank_mask:0xf bound_ctrl:1
	v_add_f32_dpp v76, v76, v76 row_half_mirror row_mask:0xf bank_mask:0xf bound_ctrl:1
	v_pk_mul_f32 v[80:81], v[66:67], v[74:75] op_sel_hi:[1,0] neg_lo:[0,1] neg_hi:[0,1]
	v_pk_mul_f32 v[66:67], v[66:67], v[76:77] op_sel_hi:[1,0] neg_lo:[0,1] neg_hi:[0,1]
	v_pk_fma_f32 v[80:81], v[62:63], v[92:93], v[80:81]
	v_pk_fma_f32 v[62:63], v[62:63], v[94:95], v[66:67]
	v_pk_fma_f32 v[90:91], v[70:71], v[96:97], v[80:81] op_sel_hi:[1,0,1]
	v_pk_fma_f32 v[98:99], v[70:71], v[96:97], v[62:63] op_sel:[0,1,0]
	v_pk_mul_f32 v[62:63], v[68:69], v[74:75] op_sel_hi:[1,0] neg_lo:[0,1] neg_hi:[0,1]
	v_pk_mul_f32 v[170:171], v[68:69], v[76:77] op_sel_hi:[1,0] neg_lo:[0,1] neg_hi:[0,1]
	v_pk_fma_f32 v[62:63], v[64:65], v[100:101], v[62:63]
	v_pk_fma_f32 v[170:171], v[64:65], v[102:103], v[170:171]
	v_pk_fma_f32 v[92:93], v[72:73], v[96:97], v[62:63] op_sel_hi:[1,0,1]
	v_pk_fma_f32 v[100:101], v[72:73], v[96:97], v[170:171] op_sel:[0,1,0]
	v_pk_mul_f32 v[62:63], v[54:55], v[74:75] op_sel_hi:[1,0] neg_lo:[0,1] neg_hi:[0,1]
	v_pk_mul_f32 v[54:55], v[54:55], v[76:77] op_sel_hi:[1,0] neg_lo:[0,1] neg_hi:[0,1]
	v_pk_fma_f32 v[62:63], v[50:51], v[104:105], v[62:63]
	v_pk_fma_f32 v[50:51], v[50:51], v[108:109], v[54:55]
	v_pk_fma_f32 v[94:95], v[58:59], v[96:97], v[62:63] op_sel_hi:[1,0,1]
	v_pk_fma_f32 v[102:103], v[58:59], v[96:97], v[50:51] op_sel:[0,1,0]
	v_pk_mul_f32 v[50:51], v[56:57], v[74:75] op_sel_hi:[1,0] neg_lo:[0,1] neg_hi:[0,1]
	v_pk_mul_f32 v[170:171], v[56:57], v[76:77] op_sel_hi:[1,0] neg_lo:[0,1] neg_hi:[0,1]
	v_pk_fma_f32 v[50:51], v[52:53], v[110:111], v[50:51]
	v_pk_fma_f32 v[170:171], v[52:53], v[112:113], v[170:171]
	v_pk_fma_f32 v[104:105], v[60:61], v[96:97], v[170:171] op_sel:[0,1,0]
	v_pk_fma_f32 v[96:97], v[60:61], v[96:97], v[50:51] op_sel_hi:[1,0,1]
	v_pk_mul_f32 v[50:51], v[48:49], v[92:93]
	v_pk_mul_f32 v[48:49], v[48:49], v[100:101]
	v_pk_fma_f32 v[50:51], v[46:47], v[90:91], v[50:51]
	v_pk_fma_f32 v[46:47], v[46:47], v[98:99], v[48:49]
	v_pk_fma_f32 v[48:49], v[44:45], v[96:97], v[50:51]
	v_pk_fma_f32 v[44:45], v[44:45], v[104:105], v[46:47]
	v_pk_fma_f32 v[48:49], v[42:43], v[94:95], v[48:49]
	v_pk_fma_f32 v[42:43], v[42:43], v[102:103], v[44:45]
	v_add_f32_e32 v163, v48, v49
	v_add_f32_e32 v164, v42, v43
	v_cndmask_b32_e64 v166, v159, v157, s[98:99]
	v_cndmask_b32_e64 v168, v163, v161, s[98:99]
	v_cndmask_b32_e64 v172, v160, v158, s[98:99]
	v_cndmask_b32_e64 v240, v164, v162, s[98:99]
	v_cndmask_b32_e64 v165, v157, v159, s[98:99]
	v_cndmask_b32_e64 v167, v161, v163, s[98:99]
	v_cndmask_b32_e64 v169, v158, v160, s[98:99]
	v_cndmask_b32_e64 v187, v162, v164, s[98:99]
	v_add_f32_dpp v165, v166, v165 quad_perm:[1,0,3,2] row_mask:0xf bank_mask:0xf bound_ctrl:1
	v_add_f32_dpp v167, v168, v167 quad_perm:[1,0,3,2] row_mask:0xf bank_mask:0xf bound_ctrl:1
	v_add_f32_dpp v169, v172, v169 quad_perm:[1,0,3,2] row_mask:0xf bank_mask:0xf bound_ctrl:1
	v_add_f32_dpp v187, v240, v187 quad_perm:[1,0,3,2] row_mask:0xf bank_mask:0xf bound_ctrl:1
	v_cndmask_b32_e64 v166, v167, v165, s[100:101]
	v_cndmask_b32_e64 v172, v187, v169, s[100:101]
	v_cndmask_b32_e64 v165, v165, v167, s[100:101]
	v_cndmask_b32_e64 v169, v169, v187, s[100:101]
	v_add_f32_dpp v165, v166, v165 quad_perm:[2,3,0,1] row_mask:0xf bank_mask:0xf bound_ctrl:1
	v_add_f32_dpp v169, v172, v169 quad_perm:[2,3,0,1] row_mask:0xf bank_mask:0xf bound_ctrl:1
	s_nop 0
	v_add_f32_dpp v165, v165, v165 row_shr:4 row_mask:0xf bank_mask:0xf bound_ctrl:1
	v_add_f32_dpp v169, v169, v169 row_shr:4 row_mask:0xf bank_mask:0xf bound_ctrl:1
	s_mov_b64 s[72:73], exec
	s_mov_b32 exec_lo, 0xf0f0f0f0
	s_mov_b32 exec_hi, 0xf0f0f0f0
	ds_write_b32 v253, v165
	ds_write_b32 v253, v169 offset:128
	s_mov_b64 exec, s[72:73]
	s_branch .LBB0_2516
